# scan chunk loop: next chunk address computation moved in front of the chunk barrier
# baseline (speedup 1.0000x reference)
; #define LAS __attribute__((address_space(3)))
; #define SC_LD(S, X) do { const LAS float* q_ = sb + (S) * STEPF; X##kk = *(const LAS f32x4*)(q_ + lo_own); X##wr = *(const LAS f32x4*)(q_ + lo_oth); X##w = *(const LAS f32x4*)(q_ + 128 + 4 * cgp); \
;         X##k = *(const LAS f32x4*)(q_ + 192 + 4 * cgp); X##b = *(const LAS f32x4*)(q_ + 256 + 4 * cgp); X##vk = *(const LAS f32x2*)(q_ + 320 + 2 * row); } while (0)
; __device__ __forceinline__ void scan_phase(const Ctx& F, const float* sbg) {
;     ...
;             for (int ch = 0; ch < NCH; ++ch) {
;                 const LAS float* sb = bufs + (ch & 1) * (T * STEPF); LAS float* yb = ybufs + (ch & 1) * (T * 16) + rl;
;                 f32x4 Akk, Awr, Aw, Ak, Ab, Bkk, Bwr, Bw, Bk, Bb; f32x2 Avk, Bvk;
;     ...
;                 SC_LD(0, A);
; #pragma unroll
;                 for (int s = 0; s < T; s += 2) { SC_LD(s + 1, B); SC_ST(s, A); if (s + 2 < T) SC_LD(s + 2, A); SC_ST(s + 1, B); }
;     ...
;                 asm volatile("s_waitcnt lgkmcnt(0)\n\ts_barrier" ::: "memory");
.LBB0_694:
	s_and_b32 s0, s22, 1
	s_mul_i32 s1, s0, 0xe000
	v_lshl_add_u32 v86, v171, 2, s1
	v_lshl_add_u32 v84, v173, 2, s1
	v_lshl_add_u32 v83, v1, 2, s1
	v_lshl_add_u32 v85, v82, 2, s1
	v_lshl_add_u32 v94, s0, 11, v206
	v_add_u32_e32 v94, v94, v198
.Lscan_chunk:
	ds_read_b128 v[18:21], v86 offset:0
	ds_read_b128 v[22:25], v84 offset:0
	ds_read_b128 v[26:29], v83 offset:512
	ds_read_b128 v[30:33], v83 offset:768
	ds_read_b128 v[34:37], v83 offset:1024
	ds_read_b64 v[38:39], v85 offset:1280
	ds_read_b128 v[40:43], v86 offset:1792
	ds_read_b128 v[44:47], v84 offset:1792
	ds_read_b128 v[48:51], v83 offset:2304
	ds_read_b128 v[52:55], v83 offset:2560
	ds_read_b128 v[56:59], v83 offset:2816
	ds_read_b64 v[60:61], v85 offset:3072
	s_waitcnt lgkmcnt(6)
	v_pk_mul_f32 v[4:5], v[18:19], v[16:17]
	v_pk_mul_f32 v[6:7], v[22:23], v[16:17]
	v_pk_fma_f32 v[4:5], v[20:21], v[78:79], v[4:5]
	v_pk_fma_f32 v[6:7], v[24:25], v[78:79], v[6:7]
	v_add_f32_e32 v2, v4, v5
	v_pk_add_f32 v[8:9], v[6:7], v[6:7] op_sel:[0,1] op_sel_hi:[1,0]
	v_pk_mul_f32 v[14:15], v[26:27], v[16:17]
	v_pk_mul_f32 v[62:63], v[28:29], v[78:79]
	v_add_f32_dpp v10, v8, v2 quad_perm:[1,0,3,2] row_mask:0xf bank_mask:0xf bound_ctrl:1
	v_pk_fma_f32 v[14:15], v[30:31], v[38:39], v[14:15] op_sel_hi:[1,0,1]
	v_pk_fma_f32 v[62:63], v[32:33], v[38:39], v[62:63] op_sel_hi:[1,0,1]
	v_add_f32_dpp v10, v10, v10 quad_perm:[2,3,0,1] row_mask:0xf bank_mask:0xf bound_ctrl:1
	ds_read_b128 v[100:103], v86 offset:3584
	ds_read_b128 v[104:107], v84 offset:3584
	v_add_f32_dpp v10, v10, v10 row_ror:4 row_mask:0xf bank_mask:0xf bound_ctrl:1
	ds_read_b128 v[108:111], v83 offset:4096
	ds_read_b128 v[112:115], v83 offset:4352
	v_add_f32_dpp v11, v10, v10 row_ror:8 row_mask:0xf bank_mask:0xf bound_ctrl:1
	ds_read_b128 v[116:119], v83 offset:4608
	ds_read_b64 v[120:121], v85 offset:4864
	v_mov_b32_dpp v12, v11 quad_perm:[0,0,2,2] row_mask:0xf bank_mask:0xf bound_ctrl:1
	v_pk_fma_f32 v[16:17], v[34:35], v[12:13], v[14:15] op_sel_hi:[1,0,1] neg_lo:[1,0,0] neg_hi:[1,0,0]
	v_pk_fma_f32 v[78:79], v[36:37], v[12:13], v[62:63] op_sel_hi:[1,0,1] neg_lo:[1,0,0] neg_hi:[1,0,0]
	v_fmac_f32_e32 v11, v38, v39
	v_cndmask_b32_e64 v87, v87, v11, s[4:5]
	s_waitcnt lgkmcnt(6)
	v_pk_mul_f32 v[4:5], v[40:41], v[16:17]
	v_pk_mul_f32 v[6:7], v[44:45], v[16:17]
	v_pk_fma_f32 v[4:5], v[42:43], v[78:79], v[4:5]
	v_pk_fma_f32 v[6:7], v[46:47], v[78:79], v[6:7]
	v_add_f32_e32 v2, v4, v5
	v_pk_add_f32 v[8:9], v[6:7], v[6:7] op_sel:[0,1] op_sel_hi:[1,0]
	v_pk_mul_f32 v[14:15], v[48:49], v[16:17]
	v_pk_mul_f32 v[62:63], v[50:51], v[78:79]
	v_add_f32_dpp v10, v8, v2 quad_perm:[1,0,3,2] row_mask:0xf bank_mask:0xf bound_ctrl:1
	v_pk_fma_f32 v[14:15], v[52:53], v[60:61], v[14:15] op_sel_hi:[1,0,1]
	v_pk_fma_f32 v[62:63], v[54:55], v[60:61], v[62:63] op_sel_hi:[1,0,1]
	v_add_f32_dpp v10, v10, v10 quad_perm:[2,3,0,1] row_mask:0xf bank_mask:0xf bound_ctrl:1
	ds_read_b128 v[122:125], v86 offset:5376
	ds_read_b128 v[126:129], v84 offset:5376
	v_add_f32_dpp v10, v10, v10 row_ror:4 row_mask:0xf bank_mask:0xf bound_ctrl:1
	ds_read_b128 v[130:133], v83 offset:5888
	ds_read_b128 v[134:137], v83 offset:6144
	v_add_f32_dpp v11, v10, v10 row_ror:8 row_mask:0xf bank_mask:0xf bound_ctrl:1
	ds_read_b128 v[138:141], v83 offset:6400
	ds_read_b64 v[142:143], v85 offset:6656
	v_mov_b32_dpp v12, v11 quad_perm:[0,0,2,2] row_mask:0xf bank_mask:0xf bound_ctrl:1
	v_pk_fma_f32 v[16:17], v[56:57], v[12:13], v[14:15] op_sel_hi:[1,0,1] neg_lo:[1,0,0] neg_hi:[1,0,0]
	v_pk_fma_f32 v[78:79], v[58:59], v[12:13], v[62:63] op_sel_hi:[1,0,1] neg_lo:[1,0,0] neg_hi:[1,0,0]
	v_fmac_f32_e32 v11, v60, v61
	v_cndmask_b32_e64 v87, v87, v11, s[6:7]
	s_waitcnt lgkmcnt(6)
	v_pk_mul_f32 v[4:5], v[100:101], v[16:17]
	v_pk_mul_f32 v[6:7], v[104:105], v[16:17]
	v_pk_fma_f32 v[4:5], v[102:103], v[78:79], v[4:5]
	v_pk_fma_f32 v[6:7], v[106:107], v[78:79], v[6:7]
	v_add_f32_e32 v2, v4, v5
	v_pk_add_f32 v[8:9], v[6:7], v[6:7] op_sel:[0,1] op_sel_hi:[1,0]
	v_pk_mul_f32 v[14:15], v[108:109], v[16:17]
	v_pk_mul_f32 v[62:63], v[110:111], v[78:79]
	v_add_f32_dpp v10, v8, v2 quad_perm:[1,0,3,2] row_mask:0xf bank_mask:0xf bound_ctrl:1
	v_pk_fma_f32 v[14:15], v[112:113], v[120:121], v[14:15] op_sel_hi:[1,0,1]
	v_pk_fma_f32 v[62:63], v[114:115], v[120:121], v[62:63] op_sel_hi:[1,0,1]
	v_add_f32_dpp v10, v10, v10 quad_perm:[2,3,0,1] row_mask:0xf bank_mask:0xf bound_ctrl:1
	ds_read_b128 v[18:21], v86 offset:7168
	ds_read_b128 v[22:25], v84 offset:7168
	v_add_f32_dpp v10, v10, v10 row_ror:4 row_mask:0xf bank_mask:0xf bound_ctrl:1
	ds_read_b128 v[26:29], v83 offset:7680
	ds_read_b128 v[30:33], v83 offset:7936
	v_add_f32_dpp v11, v10, v10 row_ror:8 row_mask:0xf bank_mask:0xf bound_ctrl:1
	ds_read_b128 v[34:37], v83 offset:8192
	ds_read_b64 v[38:39], v85 offset:8448
	v_mov_b32_dpp v12, v11 quad_perm:[0,0,2,2] row_mask:0xf bank_mask:0xf bound_ctrl:1
	v_pk_fma_f32 v[16:17], v[116:117], v[12:13], v[14:15] op_sel_hi:[1,0,1] neg_lo:[1,0,0] neg_hi:[1,0,0]
	v_pk_fma_f32 v[78:79], v[118:119], v[12:13], v[62:63] op_sel_hi:[1,0,1] neg_lo:[1,0,0] neg_hi:[1,0,0]
	v_fmac_f32_e32 v11, v120, v121
	v_cndmask_b32_e64 v87, v87, v11, s[8:9]
	s_waitcnt lgkmcnt(6)
; #define SC_LD(S, X) do { const LAS float* q_ = sb + (S) * STEPF; X##kk = *(const LAS f32x4*)(q_ + lo_own); X##wr = *(const LAS f32x4*)(q_ + lo_oth); X##w = *(const LAS f32x4*)(q_ + 128 + 4 * cgp); \
;         X##k = *(const LAS f32x4*)(q_ + 192 + 4 * cgp); X##b = *(const LAS f32x4*)(q_ + 256 + 4 * cgp); X##vk = *(const LAS f32x2*)(q_ + 320 + 2 * row); } while (0)
; __device__ __forceinline__ void scan_phase(const Ctx& F, const float* sbg) {
;     ...
;                 SC_LD(0, A);
; #pragma unroll
;                 for (int s = 0; s < T; s += 2) { SC_LD(s + 1, B); SC_ST(s, A); if (s + 2 < T) SC_LD(s + 2, A); SC_ST(s + 1, B); }
	v_pk_mul_f32 v[4:5], v[122:123], v[16:17]
	v_pk_mul_f32 v[6:7], v[126:127], v[16:17]
	v_pk_fma_f32 v[4:5], v[124:125], v[78:79], v[4:5]
	v_pk_fma_f32 v[6:7], v[128:129], v[78:79], v[6:7]
	v_add_f32_e32 v2, v4, v5
	v_pk_add_f32 v[8:9], v[6:7], v[6:7] op_sel:[0,1] op_sel_hi:[1,0]
	v_pk_mul_f32 v[14:15], v[130:131], v[16:17]
	v_pk_mul_f32 v[62:63], v[132:133], v[78:79]
	v_add_f32_dpp v10, v8, v2 quad_perm:[1,0,3,2] row_mask:0xf bank_mask:0xf bound_ctrl:1
	v_pk_fma_f32 v[14:15], v[134:135], v[142:143], v[14:15] op_sel_hi:[1,0,1]
	v_pk_fma_f32 v[62:63], v[136:137], v[142:143], v[62:63] op_sel_hi:[1,0,1]
	v_add_f32_dpp v10, v10, v10 quad_perm:[2,3,0,1] row_mask:0xf bank_mask:0xf bound_ctrl:1
	ds_read_b128 v[40:43], v86 offset:8960
	ds_read_b128 v[44:47], v84 offset:8960
	v_add_f32_dpp v10, v10, v10 row_ror:4 row_mask:0xf bank_mask:0xf bound_ctrl:1
	ds_read_b128 v[48:51], v83 offset:9472
	ds_read_b128 v[52:55], v83 offset:9728
	v_add_f32_dpp v11, v10, v10 row_ror:8 row_mask:0xf bank_mask:0xf bound_ctrl:1
	ds_read_b128 v[56:59], v83 offset:9984
	ds_read_b64 v[60:61], v85 offset:10240
	v_mov_b32_dpp v12, v11 quad_perm:[0,0,2,2] row_mask:0xf bank_mask:0xf bound_ctrl:1
	v_pk_fma_f32 v[16:17], v[138:139], v[12:13], v[14:15] op_sel_hi:[1,0,1] neg_lo:[1,0,0] neg_hi:[1,0,0]
	v_pk_fma_f32 v[78:79], v[140:141], v[12:13], v[62:63] op_sel_hi:[1,0,1] neg_lo:[1,0,0] neg_hi:[1,0,0]
	v_fmac_f32_e32 v11, v142, v143
	v_cndmask_b32_e64 v87, v87, v11, s[10:11]
	s_waitcnt lgkmcnt(6)
	v_pk_mul_f32 v[4:5], v[18:19], v[16:17]
	v_pk_mul_f32 v[6:7], v[22:23], v[16:17]
	v_pk_fma_f32 v[4:5], v[20:21], v[78:79], v[4:5]
	v_pk_fma_f32 v[6:7], v[24:25], v[78:79], v[6:7]
	v_add_f32_e32 v2, v4, v5
	v_pk_add_f32 v[8:9], v[6:7], v[6:7] op_sel:[0,1] op_sel_hi:[1,0]
	v_pk_mul_f32 v[14:15], v[26:27], v[16:17]
	v_pk_mul_f32 v[62:63], v[28:29], v[78:79]
	v_add_f32_dpp v10, v8, v2 quad_perm:[1,0,3,2] row_mask:0xf bank_mask:0xf bound_ctrl:1
	v_pk_fma_f32 v[14:15], v[30:31], v[38:39], v[14:15] op_sel_hi:[1,0,1]
	v_pk_fma_f32 v[62:63], v[32:33], v[38:39], v[62:63] op_sel_hi:[1,0,1]
	v_add_f32_dpp v10, v10, v10 quad_perm:[2,3,0,1] row_mask:0xf bank_mask:0xf bound_ctrl:1
	ds_read_b128 v[100:103], v86 offset:10752
	ds_read_b128 v[104:107], v84 offset:10752
	v_add_f32_dpp v10, v10, v10 row_ror:4 row_mask:0xf bank_mask:0xf bound_ctrl:1
	ds_read_b128 v[108:111], v83 offset:11264
	ds_read_b128 v[112:115], v83 offset:11520
	v_add_f32_dpp v11, v10, v10 row_ror:8 row_mask:0xf bank_mask:0xf bound_ctrl:1
	ds_read_b128 v[116:119], v83 offset:11776
	ds_read_b64 v[120:121], v85 offset:12032
	v_mov_b32_dpp v12, v11 quad_perm:[0,0,2,2] row_mask:0xf bank_mask:0xf bound_ctrl:1
	v_pk_fma_f32 v[16:17], v[34:35], v[12:13], v[14:15] op_sel_hi:[1,0,1] neg_lo:[1,0,0] neg_hi:[1,0,0]
	v_pk_fma_f32 v[78:79], v[36:37], v[12:13], v[62:63] op_sel_hi:[1,0,1] neg_lo:[1,0,0] neg_hi:[1,0,0]
	v_fmac_f32_e32 v11, v38, v39
	v_cndmask_b32_e64 v87, v87, v11, s[12:13]
	s_waitcnt lgkmcnt(6)
	v_pk_mul_f32 v[4:5], v[40:41], v[16:17]
	v_pk_mul_f32 v[6:7], v[44:45], v[16:17]
	v_pk_fma_f32 v[4:5], v[42:43], v[78:79], v[4:5]
	v_pk_fma_f32 v[6:7], v[46:47], v[78:79], v[6:7]
	v_add_f32_e32 v2, v4, v5
	v_pk_add_f32 v[8:9], v[6:7], v[6:7] op_sel:[0,1] op_sel_hi:[1,0]
	v_pk_mul_f32 v[14:15], v[48:49], v[16:17]
	v_pk_mul_f32 v[62:63], v[50:51], v[78:79]
	v_add_f32_dpp v10, v8, v2 quad_perm:[1,0,3,2] row_mask:0xf bank_mask:0xf bound_ctrl:1
	v_pk_fma_f32 v[14:15], v[52:53], v[60:61], v[14:15] op_sel_hi:[1,0,1]
	v_pk_fma_f32 v[62:63], v[54:55], v[60:61], v[62:63] op_sel_hi:[1,0,1]
	v_add_f32_dpp v10, v10, v10 quad_perm:[2,3,0,1] row_mask:0xf bank_mask:0xf bound_ctrl:1
	ds_read_b128 v[122:125], v86 offset:12544
	ds_read_b128 v[126:129], v84 offset:12544
	v_add_f32_dpp v10, v10, v10 row_ror:4 row_mask:0xf bank_mask:0xf bound_ctrl:1
	ds_read_b128 v[130:133], v83 offset:13056
	ds_read_b128 v[134:137], v83 offset:13312
	v_add_f32_dpp v11, v10, v10 row_ror:8 row_mask:0xf bank_mask:0xf bound_ctrl:1
	ds_read_b128 v[138:141], v83 offset:13568
	ds_read_b64 v[142:143], v85 offset:13824
	v_mov_b32_dpp v12, v11 quad_perm:[0,0,2,2] row_mask:0xf bank_mask:0xf bound_ctrl:1
	v_pk_fma_f32 v[16:17], v[56:57], v[12:13], v[14:15] op_sel_hi:[1,0,1] neg_lo:[1,0,0] neg_hi:[1,0,0]
	v_pk_fma_f32 v[78:79], v[58:59], v[12:13], v[62:63] op_sel_hi:[1,0,1] neg_lo:[1,0,0] neg_hi:[1,0,0]
	v_fmac_f32_e32 v11, v60, v61
	v_cndmask_b32_e64 v87, v87, v11, s[14:15]
	s_waitcnt lgkmcnt(6)
	v_pk_mul_f32 v[4:5], v[100:101], v[16:17]
	v_pk_mul_f32 v[6:7], v[104:105], v[16:17]
	v_pk_fma_f32 v[4:5], v[102:103], v[78:79], v[4:5]
	v_pk_fma_f32 v[6:7], v[106:107], v[78:79], v[6:7]
	v_add_f32_e32 v2, v4, v5
	v_pk_add_f32 v[8:9], v[6:7], v[6:7] op_sel:[0,1] op_sel_hi:[1,0]
	v_pk_mul_f32 v[14:15], v[108:109], v[16:17]
	v_pk_mul_f32 v[62:63], v[110:111], v[78:79]
	v_add_f32_dpp v10, v8, v2 quad_perm:[1,0,3,2] row_mask:0xf bank_mask:0xf bound_ctrl:1
	v_pk_fma_f32 v[14:15], v[112:113], v[120:121], v[14:15] op_sel_hi:[1,0,1]
	v_pk_fma_f32 v[62:63], v[114:115], v[120:121], v[62:63] op_sel_hi:[1,0,1]
	v_add_f32_dpp v10, v10, v10 quad_perm:[2,3,0,1] row_mask:0xf bank_mask:0xf bound_ctrl:1
	ds_read_b128 v[18:21], v86 offset:14336
	ds_read_b128 v[22:25], v84 offset:14336
	v_add_f32_dpp v10, v10, v10 row_ror:4 row_mask:0xf bank_mask:0xf bound_ctrl:1
	ds_read_b128 v[26:29], v83 offset:14848
	ds_read_b128 v[30:33], v83 offset:15104
	v_add_f32_dpp v11, v10, v10 row_ror:8 row_mask:0xf bank_mask:0xf bound_ctrl:1
	ds_read_b128 v[34:37], v83 offset:15360
	ds_read_b64 v[38:39], v85 offset:15616
	v_mov_b32_dpp v12, v11 quad_perm:[0,0,2,2] row_mask:0xf bank_mask:0xf bound_ctrl:1
	v_pk_fma_f32 v[16:17], v[116:117], v[12:13], v[14:15] op_sel_hi:[1,0,1] neg_lo:[1,0,0] neg_hi:[1,0,0]
	v_pk_fma_f32 v[78:79], v[118:119], v[12:13], v[62:63] op_sel_hi:[1,0,1] neg_lo:[1,0,0] neg_hi:[1,0,0]
	v_fmac_f32_e32 v11, v120, v121
	v_cndmask_b32_e64 v87, v87, v11, s[16:17]
	s_waitcnt lgkmcnt(6)
; #define SC_LD(S, X) do { const LAS float* q_ = sb + (S) * STEPF; X##kk = *(const LAS f32x4*)(q_ + lo_own); X##wr = *(const LAS f32x4*)(q_ + lo_oth); X##w = *(const LAS f32x4*)(q_ + 128 + 4 * cgp); \
;         X##k = *(const LAS f32x4*)(q_ + 192 + 4 * cgp); X##b = *(const LAS f32x4*)(q_ + 256 + 4 * cgp); X##vk = *(const LAS f32x2*)(q_ + 320 + 2 * row); } while (0)
; __device__ __forceinline__ void scan_phase(const Ctx& F, const float* sbg) {
;     ...
;                 SC_LD(0, A);
; #pragma unroll
;                 for (int s = 0; s < T; s += 2) { SC_LD(s + 1, B); SC_ST(s, A); if (s + 2 < T) SC_LD(s + 2, A); SC_ST(s + 1, B); }
	v_pk_mul_f32 v[4:5], v[122:123], v[16:17]
	v_pk_mul_f32 v[6:7], v[126:127], v[16:17]
	v_pk_fma_f32 v[4:5], v[124:125], v[78:79], v[4:5]
	v_pk_fma_f32 v[6:7], v[128:129], v[78:79], v[6:7]
	v_add_f32_e32 v2, v4, v5
	v_pk_add_f32 v[8:9], v[6:7], v[6:7] op_sel:[0,1] op_sel_hi:[1,0]
	v_pk_mul_f32 v[14:15], v[130:131], v[16:17]
	v_pk_mul_f32 v[62:63], v[132:133], v[78:79]
	v_add_f32_dpp v10, v8, v2 quad_perm:[1,0,3,2] row_mask:0xf bank_mask:0xf bound_ctrl:1
	v_pk_fma_f32 v[14:15], v[134:135], v[142:143], v[14:15] op_sel_hi:[1,0,1]
	v_pk_fma_f32 v[62:63], v[136:137], v[142:143], v[62:63] op_sel_hi:[1,0,1]
	v_add_f32_dpp v10, v10, v10 quad_perm:[2,3,0,1] row_mask:0xf bank_mask:0xf bound_ctrl:1
	ds_read_b128 v[40:43], v86 offset:16128
	ds_read_b128 v[44:47], v84 offset:16128
	v_add_f32_dpp v10, v10, v10 row_ror:4 row_mask:0xf bank_mask:0xf bound_ctrl:1
	ds_read_b128 v[48:51], v83 offset:16640
	ds_read_b128 v[52:55], v83 offset:16896
	v_add_f32_dpp v11, v10, v10 row_ror:8 row_mask:0xf bank_mask:0xf bound_ctrl:1
	ds_read_b128 v[56:59], v83 offset:17152
	ds_read_b64 v[60:61], v85 offset:17408
	v_mov_b32_dpp v12, v11 quad_perm:[0,0,2,2] row_mask:0xf bank_mask:0xf bound_ctrl:1
	v_pk_fma_f32 v[16:17], v[138:139], v[12:13], v[14:15] op_sel_hi:[1,0,1] neg_lo:[1,0,0] neg_hi:[1,0,0]
	v_pk_fma_f32 v[78:79], v[140:141], v[12:13], v[62:63] op_sel_hi:[1,0,1] neg_lo:[1,0,0] neg_hi:[1,0,0]
	v_fmac_f32_e32 v11, v142, v143
	v_cndmask_b32_e64 v87, v87, v11, s[18:19]
	s_and_saveexec_b64 s[0:1], s[2:3]
	ds_write_b32 v94, v87
	s_or_b64 exec, exec, s[0:1]
	s_waitcnt lgkmcnt(6)
	v_pk_mul_f32 v[4:5], v[18:19], v[16:17]
	v_pk_mul_f32 v[6:7], v[22:23], v[16:17]
	v_pk_fma_f32 v[4:5], v[20:21], v[78:79], v[4:5]
	v_pk_fma_f32 v[6:7], v[24:25], v[78:79], v[6:7]
	v_add_f32_e32 v2, v4, v5
	v_pk_add_f32 v[8:9], v[6:7], v[6:7] op_sel:[0,1] op_sel_hi:[1,0]
	v_pk_mul_f32 v[14:15], v[26:27], v[16:17]
	v_pk_mul_f32 v[62:63], v[28:29], v[78:79]
	v_add_f32_dpp v10, v8, v2 quad_perm:[1,0,3,2] row_mask:0xf bank_mask:0xf bound_ctrl:1
	v_pk_fma_f32 v[14:15], v[30:31], v[38:39], v[14:15] op_sel_hi:[1,0,1]
	v_pk_fma_f32 v[62:63], v[32:33], v[38:39], v[62:63] op_sel_hi:[1,0,1]
	v_add_f32_dpp v10, v10, v10 quad_perm:[2,3,0,1] row_mask:0xf bank_mask:0xf bound_ctrl:1
	ds_read_b128 v[100:103], v86 offset:17920
	ds_read_b128 v[104:107], v84 offset:17920
	v_add_f32_dpp v10, v10, v10 row_ror:4 row_mask:0xf bank_mask:0xf bound_ctrl:1
	ds_read_b128 v[108:111], v83 offset:18432
	ds_read_b128 v[112:115], v83 offset:18688
	v_add_f32_dpp v11, v10, v10 row_ror:8 row_mask:0xf bank_mask:0xf bound_ctrl:1
	ds_read_b128 v[116:119], v83 offset:18944
	ds_read_b64 v[120:121], v85 offset:19200
	v_mov_b32_dpp v12, v11 quad_perm:[0,0,2,2] row_mask:0xf bank_mask:0xf bound_ctrl:1
	v_pk_fma_f32 v[16:17], v[34:35], v[12:13], v[14:15] op_sel_hi:[1,0,1] neg_lo:[1,0,0] neg_hi:[1,0,0]
	v_pk_fma_f32 v[78:79], v[36:37], v[12:13], v[62:63] op_sel_hi:[1,0,1] neg_lo:[1,0,0] neg_hi:[1,0,0]
	v_fmac_f32_e32 v11, v38, v39
	v_cndmask_b32_e64 v87, v87, v11, s[4:5]
	s_waitcnt lgkmcnt(6)
	v_pk_mul_f32 v[4:5], v[40:41], v[16:17]
	v_pk_mul_f32 v[6:7], v[44:45], v[16:17]
	v_pk_fma_f32 v[4:5], v[42:43], v[78:79], v[4:5]
	v_pk_fma_f32 v[6:7], v[46:47], v[78:79], v[6:7]
	v_add_f32_e32 v2, v4, v5
	v_pk_add_f32 v[8:9], v[6:7], v[6:7] op_sel:[0,1] op_sel_hi:[1,0]
	v_pk_mul_f32 v[14:15], v[48:49], v[16:17]
	v_pk_mul_f32 v[62:63], v[50:51], v[78:79]
	v_add_f32_dpp v10, v8, v2 quad_perm:[1,0,3,2] row_mask:0xf bank_mask:0xf bound_ctrl:1
	v_pk_fma_f32 v[14:15], v[52:53], v[60:61], v[14:15] op_sel_hi:[1,0,1]
	v_pk_fma_f32 v[62:63], v[54:55], v[60:61], v[62:63] op_sel_hi:[1,0,1]
	v_add_f32_dpp v10, v10, v10 quad_perm:[2,3,0,1] row_mask:0xf bank_mask:0xf bound_ctrl:1
	ds_read_b128 v[122:125], v86 offset:19712
	ds_read_b128 v[126:129], v84 offset:19712
	v_add_f32_dpp v10, v10, v10 row_ror:4 row_mask:0xf bank_mask:0xf bound_ctrl:1
	ds_read_b128 v[130:133], v83 offset:20224
	ds_read_b128 v[134:137], v83 offset:20480
	v_add_f32_dpp v11, v10, v10 row_ror:8 row_mask:0xf bank_mask:0xf bound_ctrl:1
	ds_read_b128 v[138:141], v83 offset:20736
	ds_read_b64 v[142:143], v85 offset:20992
	v_mov_b32_dpp v12, v11 quad_perm:[0,0,2,2] row_mask:0xf bank_mask:0xf bound_ctrl:1
	v_pk_fma_f32 v[16:17], v[56:57], v[12:13], v[14:15] op_sel_hi:[1,0,1] neg_lo:[1,0,0] neg_hi:[1,0,0]
	v_pk_fma_f32 v[78:79], v[58:59], v[12:13], v[62:63] op_sel_hi:[1,0,1] neg_lo:[1,0,0] neg_hi:[1,0,0]
	v_fmac_f32_e32 v11, v60, v61
	v_cndmask_b32_e64 v87, v87, v11, s[6:7]
	s_waitcnt lgkmcnt(6)
	v_pk_mul_f32 v[4:5], v[100:101], v[16:17]
	v_pk_mul_f32 v[6:7], v[104:105], v[16:17]
	v_pk_fma_f32 v[4:5], v[102:103], v[78:79], v[4:5]
	v_pk_fma_f32 v[6:7], v[106:107], v[78:79], v[6:7]
	v_add_f32_e32 v2, v4, v5
	v_pk_add_f32 v[8:9], v[6:7], v[6:7] op_sel:[0,1] op_sel_hi:[1,0]
	v_pk_mul_f32 v[14:15], v[108:109], v[16:17]
	v_pk_mul_f32 v[62:63], v[110:111], v[78:79]
	v_add_f32_dpp v10, v8, v2 quad_perm:[1,0,3,2] row_mask:0xf bank_mask:0xf bound_ctrl:1
	v_pk_fma_f32 v[14:15], v[112:113], v[120:121], v[14:15] op_sel_hi:[1,0,1]
	v_pk_fma_f32 v[62:63], v[114:115], v[120:121], v[62:63] op_sel_hi:[1,0,1]
	v_add_f32_dpp v10, v10, v10 quad_perm:[2,3,0,1] row_mask:0xf bank_mask:0xf bound_ctrl:1
	ds_read_b128 v[18:21], v86 offset:21504
	ds_read_b128 v[22:25], v84 offset:21504
	v_add_f32_dpp v10, v10, v10 row_ror:4 row_mask:0xf bank_mask:0xf bound_ctrl:1
	ds_read_b128 v[26:29], v83 offset:22016
	ds_read_b128 v[30:33], v83 offset:22272
	v_add_f32_dpp v11, v10, v10 row_ror:8 row_mask:0xf bank_mask:0xf bound_ctrl:1
	ds_read_b128 v[34:37], v83 offset:22528
	ds_read_b64 v[38:39], v85 offset:22784
	v_mov_b32_dpp v12, v11 quad_perm:[0,0,2,2] row_mask:0xf bank_mask:0xf bound_ctrl:1
	v_pk_fma_f32 v[16:17], v[116:117], v[12:13], v[14:15] op_sel_hi:[1,0,1] neg_lo:[1,0,0] neg_hi:[1,0,0]
	v_pk_fma_f32 v[78:79], v[118:119], v[12:13], v[62:63] op_sel_hi:[1,0,1] neg_lo:[1,0,0] neg_hi:[1,0,0]
	v_fmac_f32_e32 v11, v120, v121
	v_cndmask_b32_e64 v87, v87, v11, s[8:9]
	s_waitcnt lgkmcnt(6)
; #define SC_LD(S, X) do { const LAS float* q_ = sb + (S) * STEPF; X##kk = *(const LAS f32x4*)(q_ + lo_own); X##wr = *(const LAS f32x4*)(q_ + lo_oth); X##w = *(const LAS f32x4*)(q_ + 128 + 4 * cgp); \
;         X##k = *(const LAS f32x4*)(q_ + 192 + 4 * cgp); X##b = *(const LAS f32x4*)(q_ + 256 + 4 * cgp); X##vk = *(const LAS f32x2*)(q_ + 320 + 2 * row); } while (0)
; __device__ __forceinline__ void scan_phase(const Ctx& F, const float* sbg) {
;     ...
;                 SC_LD(0, A);
; #pragma unroll
;                 for (int s = 0; s < T; s += 2) { SC_LD(s + 1, B); SC_ST(s, A); if (s + 2 < T) SC_LD(s + 2, A); SC_ST(s + 1, B); }
	v_pk_mul_f32 v[4:5], v[122:123], v[16:17]
	v_pk_mul_f32 v[6:7], v[126:127], v[16:17]
	v_pk_fma_f32 v[4:5], v[124:125], v[78:79], v[4:5]
	v_pk_fma_f32 v[6:7], v[128:129], v[78:79], v[6:7]
	v_add_f32_e32 v2, v4, v5
	v_pk_add_f32 v[8:9], v[6:7], v[6:7] op_sel:[0,1] op_sel_hi:[1,0]
	v_pk_mul_f32 v[14:15], v[130:131], v[16:17]
	v_pk_mul_f32 v[62:63], v[132:133], v[78:79]
	v_add_f32_dpp v10, v8, v2 quad_perm:[1,0,3,2] row_mask:0xf bank_mask:0xf bound_ctrl:1
	v_pk_fma_f32 v[14:15], v[134:135], v[142:143], v[14:15] op_sel_hi:[1,0,1]
	v_pk_fma_f32 v[62:63], v[136:137], v[142:143], v[62:63] op_sel_hi:[1,0,1]
	v_add_f32_dpp v10, v10, v10 quad_perm:[2,3,0,1] row_mask:0xf bank_mask:0xf bound_ctrl:1
	ds_read_b128 v[40:43], v86 offset:23296
	ds_read_b128 v[44:47], v84 offset:23296
	v_add_f32_dpp v10, v10, v10 row_ror:4 row_mask:0xf bank_mask:0xf bound_ctrl:1
	ds_read_b128 v[48:51], v83 offset:23808
	ds_read_b128 v[52:55], v83 offset:24064
	v_add_f32_dpp v11, v10, v10 row_ror:8 row_mask:0xf bank_mask:0xf bound_ctrl:1
	ds_read_b128 v[56:59], v83 offset:24320
	ds_read_b64 v[60:61], v85 offset:24576
	v_mov_b32_dpp v12, v11 quad_perm:[0,0,2,2] row_mask:0xf bank_mask:0xf bound_ctrl:1
	v_pk_fma_f32 v[16:17], v[138:139], v[12:13], v[14:15] op_sel_hi:[1,0,1] neg_lo:[1,0,0] neg_hi:[1,0,0]
	v_pk_fma_f32 v[78:79], v[140:141], v[12:13], v[62:63] op_sel_hi:[1,0,1] neg_lo:[1,0,0] neg_hi:[1,0,0]
	v_fmac_f32_e32 v11, v142, v143
	v_cndmask_b32_e64 v87, v87, v11, s[10:11]
	s_waitcnt lgkmcnt(6)
	v_pk_mul_f32 v[4:5], v[18:19], v[16:17]
	v_pk_mul_f32 v[6:7], v[22:23], v[16:17]
	v_pk_fma_f32 v[4:5], v[20:21], v[78:79], v[4:5]
	v_pk_fma_f32 v[6:7], v[24:25], v[78:79], v[6:7]
	v_add_f32_e32 v2, v4, v5
	v_pk_add_f32 v[8:9], v[6:7], v[6:7] op_sel:[0,1] op_sel_hi:[1,0]
	v_pk_mul_f32 v[14:15], v[26:27], v[16:17]
	v_pk_mul_f32 v[62:63], v[28:29], v[78:79]
	v_add_f32_dpp v10, v8, v2 quad_perm:[1,0,3,2] row_mask:0xf bank_mask:0xf bound_ctrl:1
	v_pk_fma_f32 v[14:15], v[30:31], v[38:39], v[14:15] op_sel_hi:[1,0,1]
	v_pk_fma_f32 v[62:63], v[32:33], v[38:39], v[62:63] op_sel_hi:[1,0,1]
	v_add_f32_dpp v10, v10, v10 quad_perm:[2,3,0,1] row_mask:0xf bank_mask:0xf bound_ctrl:1
	ds_read_b128 v[100:103], v86 offset:25088
	ds_read_b128 v[104:107], v84 offset:25088
	v_add_f32_dpp v10, v10, v10 row_ror:4 row_mask:0xf bank_mask:0xf bound_ctrl:1
	ds_read_b128 v[108:111], v83 offset:25600
	ds_read_b128 v[112:115], v83 offset:25856
	v_add_f32_dpp v11, v10, v10 row_ror:8 row_mask:0xf bank_mask:0xf bound_ctrl:1
	ds_read_b128 v[116:119], v83 offset:26112
	ds_read_b64 v[120:121], v85 offset:26368
	v_mov_b32_dpp v12, v11 quad_perm:[0,0,2,2] row_mask:0xf bank_mask:0xf bound_ctrl:1
	v_pk_fma_f32 v[16:17], v[34:35], v[12:13], v[14:15] op_sel_hi:[1,0,1] neg_lo:[1,0,0] neg_hi:[1,0,0]
	v_pk_fma_f32 v[78:79], v[36:37], v[12:13], v[62:63] op_sel_hi:[1,0,1] neg_lo:[1,0,0] neg_hi:[1,0,0]
	v_fmac_f32_e32 v11, v38, v39
	v_cndmask_b32_e64 v87, v87, v11, s[12:13]
	s_waitcnt lgkmcnt(6)
	v_pk_mul_f32 v[4:5], v[40:41], v[16:17]
	v_pk_mul_f32 v[6:7], v[44:45], v[16:17]
	v_pk_fma_f32 v[4:5], v[42:43], v[78:79], v[4:5]
	v_pk_fma_f32 v[6:7], v[46:47], v[78:79], v[6:7]
	v_add_f32_e32 v2, v4, v5
	v_pk_add_f32 v[8:9], v[6:7], v[6:7] op_sel:[0,1] op_sel_hi:[1,0]
	v_pk_mul_f32 v[14:15], v[48:49], v[16:17]
	v_pk_mul_f32 v[62:63], v[50:51], v[78:79]
	v_add_f32_dpp v10, v8, v2 quad_perm:[1,0,3,2] row_mask:0xf bank_mask:0xf bound_ctrl:1
	v_pk_fma_f32 v[14:15], v[52:53], v[60:61], v[14:15] op_sel_hi:[1,0,1]
	v_pk_fma_f32 v[62:63], v[54:55], v[60:61], v[62:63] op_sel_hi:[1,0,1]
	v_add_f32_dpp v10, v10, v10 quad_perm:[2,3,0,1] row_mask:0xf bank_mask:0xf bound_ctrl:1
	ds_read_b128 v[122:125], v86 offset:26880
	ds_read_b128 v[126:129], v84 offset:26880
	v_add_f32_dpp v10, v10, v10 row_ror:4 row_mask:0xf bank_mask:0xf bound_ctrl:1
	ds_read_b128 v[130:133], v83 offset:27392
	ds_read_b128 v[134:137], v83 offset:27648
	v_add_f32_dpp v11, v10, v10 row_ror:8 row_mask:0xf bank_mask:0xf bound_ctrl:1
	ds_read_b128 v[138:141], v83 offset:27904
	ds_read_b64 v[142:143], v85 offset:28160
	v_mov_b32_dpp v12, v11 quad_perm:[0,0,2,2] row_mask:0xf bank_mask:0xf bound_ctrl:1
	v_pk_fma_f32 v[16:17], v[56:57], v[12:13], v[14:15] op_sel_hi:[1,0,1] neg_lo:[1,0,0] neg_hi:[1,0,0]
	v_pk_fma_f32 v[78:79], v[58:59], v[12:13], v[62:63] op_sel_hi:[1,0,1] neg_lo:[1,0,0] neg_hi:[1,0,0]
	v_fmac_f32_e32 v11, v60, v61
	v_cndmask_b32_e64 v87, v87, v11, s[14:15]
	s_waitcnt lgkmcnt(6)
	v_pk_mul_f32 v[4:5], v[100:101], v[16:17]
	v_pk_mul_f32 v[6:7], v[104:105], v[16:17]
	v_pk_fma_f32 v[4:5], v[102:103], v[78:79], v[4:5]
	v_pk_fma_f32 v[6:7], v[106:107], v[78:79], v[6:7]
	v_add_f32_e32 v2, v4, v5
	v_pk_add_f32 v[8:9], v[6:7], v[6:7] op_sel:[0,1] op_sel_hi:[1,0]
	v_pk_mul_f32 v[14:15], v[108:109], v[16:17]
	v_pk_mul_f32 v[62:63], v[110:111], v[78:79]
	v_add_f32_dpp v10, v8, v2 quad_perm:[1,0,3,2] row_mask:0xf bank_mask:0xf bound_ctrl:1
	v_pk_fma_f32 v[14:15], v[112:113], v[120:121], v[14:15] op_sel_hi:[1,0,1]
	v_pk_fma_f32 v[62:63], v[114:115], v[120:121], v[62:63] op_sel_hi:[1,0,1]
	v_add_f32_dpp v10, v10, v10 quad_perm:[2,3,0,1] row_mask:0xf bank_mask:0xf bound_ctrl:1
	ds_read_b128 v[18:21], v86 offset:28672
	ds_read_b128 v[22:25], v84 offset:28672
	v_add_f32_dpp v10, v10, v10 row_ror:4 row_mask:0xf bank_mask:0xf bound_ctrl:1
	ds_read_b128 v[26:29], v83 offset:29184
	ds_read_b128 v[30:33], v83 offset:29440
	v_add_f32_dpp v11, v10, v10 row_ror:8 row_mask:0xf bank_mask:0xf bound_ctrl:1
	ds_read_b128 v[34:37], v83 offset:29696
	ds_read_b64 v[38:39], v85 offset:29952
	v_mov_b32_dpp v12, v11 quad_perm:[0,0,2,2] row_mask:0xf bank_mask:0xf bound_ctrl:1
	v_pk_fma_f32 v[16:17], v[116:117], v[12:13], v[14:15] op_sel_hi:[1,0,1] neg_lo:[1,0,0] neg_hi:[1,0,0]
	v_pk_fma_f32 v[78:79], v[118:119], v[12:13], v[62:63] op_sel_hi:[1,0,1] neg_lo:[1,0,0] neg_hi:[1,0,0]
	v_fmac_f32_e32 v11, v120, v121
	v_cndmask_b32_e64 v87, v87, v11, s[16:17]
	s_waitcnt lgkmcnt(6)
; #define SC_LD(S, X) do { const LAS float* q_ = sb + (S) * STEPF; X##kk = *(const LAS f32x4*)(q_ + lo_own); X##wr = *(const LAS f32x4*)(q_ + lo_oth); X##w = *(const LAS f32x4*)(q_ + 128 + 4 * cgp); \
;         X##k = *(const LAS f32x4*)(q_ + 192 + 4 * cgp); X##b = *(const LAS f32x4*)(q_ + 256 + 4 * cgp); X##vk = *(const LAS f32x2*)(q_ + 320 + 2 * row); } while (0)
; __device__ __forceinline__ void scan_phase(const Ctx& F, const float* sbg) {
;     ...
;                 SC_LD(0, A);
; #pragma unroll
;                 for (int s = 0; s < T; s += 2) { SC_LD(s + 1, B); SC_ST(s, A); if (s + 2 < T) SC_LD(s + 2, A); SC_ST(s + 1, B); }
	v_pk_mul_f32 v[4:5], v[122:123], v[16:17]
	v_pk_mul_f32 v[6:7], v[126:127], v[16:17]
	v_pk_fma_f32 v[4:5], v[124:125], v[78:79], v[4:5]
	v_pk_fma_f32 v[6:7], v[128:129], v[78:79], v[6:7]
	v_add_f32_e32 v2, v4, v5
	v_pk_add_f32 v[8:9], v[6:7], v[6:7] op_sel:[0,1] op_sel_hi:[1,0]
	v_pk_mul_f32 v[14:15], v[130:131], v[16:17]
	v_pk_mul_f32 v[62:63], v[132:133], v[78:79]
	v_add_f32_dpp v10, v8, v2 quad_perm:[1,0,3,2] row_mask:0xf bank_mask:0xf bound_ctrl:1
	v_pk_fma_f32 v[14:15], v[134:135], v[142:143], v[14:15] op_sel_hi:[1,0,1]
	v_pk_fma_f32 v[62:63], v[136:137], v[142:143], v[62:63] op_sel_hi:[1,0,1]
	v_add_f32_dpp v10, v10, v10 quad_perm:[2,3,0,1] row_mask:0xf bank_mask:0xf bound_ctrl:1
	ds_read_b128 v[40:43], v86 offset:30464
	ds_read_b128 v[44:47], v84 offset:30464
	v_add_f32_dpp v10, v10, v10 row_ror:4 row_mask:0xf bank_mask:0xf bound_ctrl:1
	ds_read_b128 v[48:51], v83 offset:30976
	ds_read_b128 v[52:55], v83 offset:31232
	v_add_f32_dpp v11, v10, v10 row_ror:8 row_mask:0xf bank_mask:0xf bound_ctrl:1
	ds_read_b128 v[56:59], v83 offset:31488
	ds_read_b64 v[60:61], v85 offset:31744
	v_mov_b32_dpp v12, v11 quad_perm:[0,0,2,2] row_mask:0xf bank_mask:0xf bound_ctrl:1
	v_pk_fma_f32 v[16:17], v[138:139], v[12:13], v[14:15] op_sel_hi:[1,0,1] neg_lo:[1,0,0] neg_hi:[1,0,0]
	v_pk_fma_f32 v[78:79], v[140:141], v[12:13], v[62:63] op_sel_hi:[1,0,1] neg_lo:[1,0,0] neg_hi:[1,0,0]
	v_fmac_f32_e32 v11, v142, v143
	v_cndmask_b32_e64 v87, v87, v11, s[18:19]
	s_and_saveexec_b64 s[0:1], s[2:3]
	ds_write_b32 v94, v87 offset:512
	s_or_b64 exec, exec, s[0:1]
	s_waitcnt lgkmcnt(6)
	v_pk_mul_f32 v[4:5], v[18:19], v[16:17]
	v_pk_mul_f32 v[6:7], v[22:23], v[16:17]
	v_pk_fma_f32 v[4:5], v[20:21], v[78:79], v[4:5]
	v_pk_fma_f32 v[6:7], v[24:25], v[78:79], v[6:7]
	v_add_f32_e32 v2, v4, v5
	v_pk_add_f32 v[8:9], v[6:7], v[6:7] op_sel:[0,1] op_sel_hi:[1,0]
	v_pk_mul_f32 v[14:15], v[26:27], v[16:17]
	v_pk_mul_f32 v[62:63], v[28:29], v[78:79]
	v_add_f32_dpp v10, v8, v2 quad_perm:[1,0,3,2] row_mask:0xf bank_mask:0xf bound_ctrl:1
	v_pk_fma_f32 v[14:15], v[30:31], v[38:39], v[14:15] op_sel_hi:[1,0,1]
	v_pk_fma_f32 v[62:63], v[32:33], v[38:39], v[62:63] op_sel_hi:[1,0,1]
	v_add_f32_dpp v10, v10, v10 quad_perm:[2,3,0,1] row_mask:0xf bank_mask:0xf bound_ctrl:1
	ds_read_b128 v[100:103], v86 offset:32256
	ds_read_b128 v[104:107], v84 offset:32256
	v_add_f32_dpp v10, v10, v10 row_ror:4 row_mask:0xf bank_mask:0xf bound_ctrl:1
	ds_read_b128 v[108:111], v83 offset:32768
	ds_read_b128 v[112:115], v83 offset:33024
	v_add_f32_dpp v11, v10, v10 row_ror:8 row_mask:0xf bank_mask:0xf bound_ctrl:1
	ds_read_b128 v[116:119], v83 offset:33280
	ds_read_b64 v[120:121], v85 offset:33536
	v_mov_b32_dpp v12, v11 quad_perm:[0,0,2,2] row_mask:0xf bank_mask:0xf bound_ctrl:1
	v_pk_fma_f32 v[16:17], v[34:35], v[12:13], v[14:15] op_sel_hi:[1,0,1] neg_lo:[1,0,0] neg_hi:[1,0,0]
	v_pk_fma_f32 v[78:79], v[36:37], v[12:13], v[62:63] op_sel_hi:[1,0,1] neg_lo:[1,0,0] neg_hi:[1,0,0]
	v_fmac_f32_e32 v11, v38, v39
	v_cndmask_b32_e64 v87, v87, v11, s[4:5]
	s_waitcnt lgkmcnt(6)
	v_pk_mul_f32 v[4:5], v[40:41], v[16:17]
	v_pk_mul_f32 v[6:7], v[44:45], v[16:17]
	v_pk_fma_f32 v[4:5], v[42:43], v[78:79], v[4:5]
	v_pk_fma_f32 v[6:7], v[46:47], v[78:79], v[6:7]
	v_add_f32_e32 v2, v4, v5
	v_pk_add_f32 v[8:9], v[6:7], v[6:7] op_sel:[0,1] op_sel_hi:[1,0]
	v_pk_mul_f32 v[14:15], v[48:49], v[16:17]
	v_pk_mul_f32 v[62:63], v[50:51], v[78:79]
	v_add_f32_dpp v10, v8, v2 quad_perm:[1,0,3,2] row_mask:0xf bank_mask:0xf bound_ctrl:1
	v_pk_fma_f32 v[14:15], v[52:53], v[60:61], v[14:15] op_sel_hi:[1,0,1]
	v_pk_fma_f32 v[62:63], v[54:55], v[60:61], v[62:63] op_sel_hi:[1,0,1]
	v_add_f32_dpp v10, v10, v10 quad_perm:[2,3,0,1] row_mask:0xf bank_mask:0xf bound_ctrl:1
	ds_read_b128 v[122:125], v86 offset:34048
	ds_read_b128 v[126:129], v84 offset:34048
	v_add_f32_dpp v10, v10, v10 row_ror:4 row_mask:0xf bank_mask:0xf bound_ctrl:1
	ds_read_b128 v[130:133], v83 offset:34560
	ds_read_b128 v[134:137], v83 offset:34816
	v_add_f32_dpp v11, v10, v10 row_ror:8 row_mask:0xf bank_mask:0xf bound_ctrl:1
	ds_read_b128 v[138:141], v83 offset:35072
	ds_read_b64 v[142:143], v85 offset:35328
	v_mov_b32_dpp v12, v11 quad_perm:[0,0,2,2] row_mask:0xf bank_mask:0xf bound_ctrl:1
	v_pk_fma_f32 v[16:17], v[56:57], v[12:13], v[14:15] op_sel_hi:[1,0,1] neg_lo:[1,0,0] neg_hi:[1,0,0]
	v_pk_fma_f32 v[78:79], v[58:59], v[12:13], v[62:63] op_sel_hi:[1,0,1] neg_lo:[1,0,0] neg_hi:[1,0,0]
	v_fmac_f32_e32 v11, v60, v61
	v_cndmask_b32_e64 v87, v87, v11, s[6:7]
	s_waitcnt lgkmcnt(6)
	v_pk_mul_f32 v[4:5], v[100:101], v[16:17]
	v_pk_mul_f32 v[6:7], v[104:105], v[16:17]
	v_pk_fma_f32 v[4:5], v[102:103], v[78:79], v[4:5]
	v_pk_fma_f32 v[6:7], v[106:107], v[78:79], v[6:7]
	v_add_f32_e32 v2, v4, v5
	v_pk_add_f32 v[8:9], v[6:7], v[6:7] op_sel:[0,1] op_sel_hi:[1,0]
	v_pk_mul_f32 v[14:15], v[108:109], v[16:17]
	v_pk_mul_f32 v[62:63], v[110:111], v[78:79]
	v_add_f32_dpp v10, v8, v2 quad_perm:[1,0,3,2] row_mask:0xf bank_mask:0xf bound_ctrl:1
	v_pk_fma_f32 v[14:15], v[112:113], v[120:121], v[14:15] op_sel_hi:[1,0,1]
	v_pk_fma_f32 v[62:63], v[114:115], v[120:121], v[62:63] op_sel_hi:[1,0,1]
	v_add_f32_dpp v10, v10, v10 quad_perm:[2,3,0,1] row_mask:0xf bank_mask:0xf bound_ctrl:1
	ds_read_b128 v[18:21], v86 offset:35840
	ds_read_b128 v[22:25], v84 offset:35840
	v_add_f32_dpp v10, v10, v10 row_ror:4 row_mask:0xf bank_mask:0xf bound_ctrl:1
	ds_read_b128 v[26:29], v83 offset:36352
	ds_read_b128 v[30:33], v83 offset:36608
	v_add_f32_dpp v11, v10, v10 row_ror:8 row_mask:0xf bank_mask:0xf bound_ctrl:1
	ds_read_b128 v[34:37], v83 offset:36864
	ds_read_b64 v[38:39], v85 offset:37120
	v_mov_b32_dpp v12, v11 quad_perm:[0,0,2,2] row_mask:0xf bank_mask:0xf bound_ctrl:1
	v_pk_fma_f32 v[16:17], v[116:117], v[12:13], v[14:15] op_sel_hi:[1,0,1] neg_lo:[1,0,0] neg_hi:[1,0,0]
	v_pk_fma_f32 v[78:79], v[118:119], v[12:13], v[62:63] op_sel_hi:[1,0,1] neg_lo:[1,0,0] neg_hi:[1,0,0]
	v_fmac_f32_e32 v11, v120, v121
	v_cndmask_b32_e64 v87, v87, v11, s[8:9]
	s_waitcnt lgkmcnt(6)
; #define SC_LD(S, X) do { const LAS float* q_ = sb + (S) * STEPF; X##kk = *(const LAS f32x4*)(q_ + lo_own); X##wr = *(const LAS f32x4*)(q_ + lo_oth); X##w = *(const LAS f32x4*)(q_ + 128 + 4 * cgp); \
;         X##k = *(const LAS f32x4*)(q_ + 192 + 4 * cgp); X##b = *(const LAS f32x4*)(q_ + 256 + 4 * cgp); X##vk = *(const LAS f32x2*)(q_ + 320 + 2 * row); } while (0)
; __device__ __forceinline__ void scan_phase(const Ctx& F, const float* sbg) {
;     ...
;                 SC_LD(0, A);
; #pragma unroll
;                 for (int s = 0; s < T; s += 2) { SC_LD(s + 1, B); SC_ST(s, A); if (s + 2 < T) SC_LD(s + 2, A); SC_ST(s + 1, B); }
	v_pk_mul_f32 v[4:5], v[122:123], v[16:17]
	v_pk_mul_f32 v[6:7], v[126:127], v[16:17]
	v_pk_fma_f32 v[4:5], v[124:125], v[78:79], v[4:5]
	v_pk_fma_f32 v[6:7], v[128:129], v[78:79], v[6:7]
	v_add_f32_e32 v2, v4, v5
	v_pk_add_f32 v[8:9], v[6:7], v[6:7] op_sel:[0,1] op_sel_hi:[1,0]
	v_pk_mul_f32 v[14:15], v[130:131], v[16:17]
	v_pk_mul_f32 v[62:63], v[132:133], v[78:79]
	v_add_f32_dpp v10, v8, v2 quad_perm:[1,0,3,2] row_mask:0xf bank_mask:0xf bound_ctrl:1
	v_pk_fma_f32 v[14:15], v[134:135], v[142:143], v[14:15] op_sel_hi:[1,0,1]
	v_pk_fma_f32 v[62:63], v[136:137], v[142:143], v[62:63] op_sel_hi:[1,0,1]
	v_add_f32_dpp v10, v10, v10 quad_perm:[2,3,0,1] row_mask:0xf bank_mask:0xf bound_ctrl:1
	ds_read_b128 v[40:43], v86 offset:37632
	ds_read_b128 v[44:47], v84 offset:37632
	v_add_f32_dpp v10, v10, v10 row_ror:4 row_mask:0xf bank_mask:0xf bound_ctrl:1
	ds_read_b128 v[48:51], v83 offset:38144
	ds_read_b128 v[52:55], v83 offset:38400
	v_add_f32_dpp v11, v10, v10 row_ror:8 row_mask:0xf bank_mask:0xf bound_ctrl:1
	ds_read_b128 v[56:59], v83 offset:38656
	ds_read_b64 v[60:61], v85 offset:38912
	v_mov_b32_dpp v12, v11 quad_perm:[0,0,2,2] row_mask:0xf bank_mask:0xf bound_ctrl:1
	v_pk_fma_f32 v[16:17], v[138:139], v[12:13], v[14:15] op_sel_hi:[1,0,1] neg_lo:[1,0,0] neg_hi:[1,0,0]
	v_pk_fma_f32 v[78:79], v[140:141], v[12:13], v[62:63] op_sel_hi:[1,0,1] neg_lo:[1,0,0] neg_hi:[1,0,0]
	v_fmac_f32_e32 v11, v142, v143
	v_cndmask_b32_e64 v87, v87, v11, s[10:11]
	s_waitcnt lgkmcnt(6)
	v_pk_mul_f32 v[4:5], v[18:19], v[16:17]
	v_pk_mul_f32 v[6:7], v[22:23], v[16:17]
	v_pk_fma_f32 v[4:5], v[20:21], v[78:79], v[4:5]
	v_pk_fma_f32 v[6:7], v[24:25], v[78:79], v[6:7]
	v_add_f32_e32 v2, v4, v5
	v_pk_add_f32 v[8:9], v[6:7], v[6:7] op_sel:[0,1] op_sel_hi:[1,0]
	v_pk_mul_f32 v[14:15], v[26:27], v[16:17]
	v_pk_mul_f32 v[62:63], v[28:29], v[78:79]
	v_add_f32_dpp v10, v8, v2 quad_perm:[1,0,3,2] row_mask:0xf bank_mask:0xf bound_ctrl:1
	v_pk_fma_f32 v[14:15], v[30:31], v[38:39], v[14:15] op_sel_hi:[1,0,1]
	v_pk_fma_f32 v[62:63], v[32:33], v[38:39], v[62:63] op_sel_hi:[1,0,1]
	v_add_f32_dpp v10, v10, v10 quad_perm:[2,3,0,1] row_mask:0xf bank_mask:0xf bound_ctrl:1
	ds_read_b128 v[100:103], v86 offset:39424
	ds_read_b128 v[104:107], v84 offset:39424
	v_add_f32_dpp v10, v10, v10 row_ror:4 row_mask:0xf bank_mask:0xf bound_ctrl:1
	ds_read_b128 v[108:111], v83 offset:39936
	ds_read_b128 v[112:115], v83 offset:40192
	v_add_f32_dpp v11, v10, v10 row_ror:8 row_mask:0xf bank_mask:0xf bound_ctrl:1
	ds_read_b128 v[116:119], v83 offset:40448
	ds_read_b64 v[120:121], v85 offset:40704
	v_mov_b32_dpp v12, v11 quad_perm:[0,0,2,2] row_mask:0xf bank_mask:0xf bound_ctrl:1
	v_pk_fma_f32 v[16:17], v[34:35], v[12:13], v[14:15] op_sel_hi:[1,0,1] neg_lo:[1,0,0] neg_hi:[1,0,0]
	v_pk_fma_f32 v[78:79], v[36:37], v[12:13], v[62:63] op_sel_hi:[1,0,1] neg_lo:[1,0,0] neg_hi:[1,0,0]
	v_fmac_f32_e32 v11, v38, v39
	v_cndmask_b32_e64 v87, v87, v11, s[12:13]
	s_waitcnt lgkmcnt(6)
	v_pk_mul_f32 v[4:5], v[40:41], v[16:17]
	v_pk_mul_f32 v[6:7], v[44:45], v[16:17]
	v_pk_fma_f32 v[4:5], v[42:43], v[78:79], v[4:5]
	v_pk_fma_f32 v[6:7], v[46:47], v[78:79], v[6:7]
	v_add_f32_e32 v2, v4, v5
	v_pk_add_f32 v[8:9], v[6:7], v[6:7] op_sel:[0,1] op_sel_hi:[1,0]
	v_pk_mul_f32 v[14:15], v[48:49], v[16:17]
	v_pk_mul_f32 v[62:63], v[50:51], v[78:79]
	v_add_f32_dpp v10, v8, v2 quad_perm:[1,0,3,2] row_mask:0xf bank_mask:0xf bound_ctrl:1
	v_pk_fma_f32 v[14:15], v[52:53], v[60:61], v[14:15] op_sel_hi:[1,0,1]
	v_pk_fma_f32 v[62:63], v[54:55], v[60:61], v[62:63] op_sel_hi:[1,0,1]
	v_add_f32_dpp v10, v10, v10 quad_perm:[2,3,0,1] row_mask:0xf bank_mask:0xf bound_ctrl:1
	ds_read_b128 v[122:125], v86 offset:41216
	ds_read_b128 v[126:129], v84 offset:41216
	v_add_f32_dpp v10, v10, v10 row_ror:4 row_mask:0xf bank_mask:0xf bound_ctrl:1
	ds_read_b128 v[130:133], v83 offset:41728
	ds_read_b128 v[134:137], v83 offset:41984
	v_add_f32_dpp v11, v10, v10 row_ror:8 row_mask:0xf bank_mask:0xf bound_ctrl:1
	ds_read_b128 v[138:141], v83 offset:42240
	ds_read_b64 v[142:143], v85 offset:42496
	v_mov_b32_dpp v12, v11 quad_perm:[0,0,2,2] row_mask:0xf bank_mask:0xf bound_ctrl:1
	v_pk_fma_f32 v[16:17], v[56:57], v[12:13], v[14:15] op_sel_hi:[1,0,1] neg_lo:[1,0,0] neg_hi:[1,0,0]
	v_pk_fma_f32 v[78:79], v[58:59], v[12:13], v[62:63] op_sel_hi:[1,0,1] neg_lo:[1,0,0] neg_hi:[1,0,0]
	v_fmac_f32_e32 v11, v60, v61
	v_cndmask_b32_e64 v87, v87, v11, s[14:15]
	s_waitcnt lgkmcnt(6)
	v_pk_mul_f32 v[4:5], v[100:101], v[16:17]
	v_pk_mul_f32 v[6:7], v[104:105], v[16:17]
	v_pk_fma_f32 v[4:5], v[102:103], v[78:79], v[4:5]
	v_pk_fma_f32 v[6:7], v[106:107], v[78:79], v[6:7]
	v_add_f32_e32 v2, v4, v5
	v_pk_add_f32 v[8:9], v[6:7], v[6:7] op_sel:[0,1] op_sel_hi:[1,0]
	v_pk_mul_f32 v[14:15], v[108:109], v[16:17]
	v_pk_mul_f32 v[62:63], v[110:111], v[78:79]
	v_add_f32_dpp v10, v8, v2 quad_perm:[1,0,3,2] row_mask:0xf bank_mask:0xf bound_ctrl:1
	v_pk_fma_f32 v[14:15], v[112:113], v[120:121], v[14:15] op_sel_hi:[1,0,1]
	v_pk_fma_f32 v[62:63], v[114:115], v[120:121], v[62:63] op_sel_hi:[1,0,1]
	v_add_f32_dpp v10, v10, v10 quad_perm:[2,3,0,1] row_mask:0xf bank_mask:0xf bound_ctrl:1
	ds_read_b128 v[18:21], v86 offset:43008
	ds_read_b128 v[22:25], v84 offset:43008
	v_add_f32_dpp v10, v10, v10 row_ror:4 row_mask:0xf bank_mask:0xf bound_ctrl:1
	ds_read_b128 v[26:29], v83 offset:43520
	ds_read_b128 v[30:33], v83 offset:43776
	v_add_f32_dpp v11, v10, v10 row_ror:8 row_mask:0xf bank_mask:0xf bound_ctrl:1
	ds_read_b128 v[34:37], v83 offset:44032
	ds_read_b64 v[38:39], v85 offset:44288
	v_mov_b32_dpp v12, v11 quad_perm:[0,0,2,2] row_mask:0xf bank_mask:0xf bound_ctrl:1
	v_pk_fma_f32 v[16:17], v[116:117], v[12:13], v[14:15] op_sel_hi:[1,0,1] neg_lo:[1,0,0] neg_hi:[1,0,0]
	v_pk_fma_f32 v[78:79], v[118:119], v[12:13], v[62:63] op_sel_hi:[1,0,1] neg_lo:[1,0,0] neg_hi:[1,0,0]
	v_fmac_f32_e32 v11, v120, v121
	v_cndmask_b32_e64 v87, v87, v11, s[16:17]
	s_waitcnt lgkmcnt(6)
; #define SC_LD(S, X) do { const LAS float* q_ = sb + (S) * STEPF; X##kk = *(const LAS f32x4*)(q_ + lo_own); X##wr = *(const LAS f32x4*)(q_ + lo_oth); X##w = *(const LAS f32x4*)(q_ + 128 + 4 * cgp); \
;         X##k = *(const LAS f32x4*)(q_ + 192 + 4 * cgp); X##b = *(const LAS f32x4*)(q_ + 256 + 4 * cgp); X##vk = *(const LAS f32x2*)(q_ + 320 + 2 * row); } while (0)
; __device__ __forceinline__ void scan_phase(const Ctx& F, const float* sbg) {
;     ...
;                 SC_LD(0, A);
; #pragma unroll
;                 for (int s = 0; s < T; s += 2) { SC_LD(s + 1, B); SC_ST(s, A); if (s + 2 < T) SC_LD(s + 2, A); SC_ST(s + 1, B); }
	v_pk_mul_f32 v[4:5], v[122:123], v[16:17]
	v_pk_mul_f32 v[6:7], v[126:127], v[16:17]
	v_pk_fma_f32 v[4:5], v[124:125], v[78:79], v[4:5]
	v_pk_fma_f32 v[6:7], v[128:129], v[78:79], v[6:7]
	v_add_f32_e32 v2, v4, v5
	v_pk_add_f32 v[8:9], v[6:7], v[6:7] op_sel:[0,1] op_sel_hi:[1,0]
	v_pk_mul_f32 v[14:15], v[130:131], v[16:17]
	v_pk_mul_f32 v[62:63], v[132:133], v[78:79]
	v_add_f32_dpp v10, v8, v2 quad_perm:[1,0,3,2] row_mask:0xf bank_mask:0xf bound_ctrl:1
	v_pk_fma_f32 v[14:15], v[134:135], v[142:143], v[14:15] op_sel_hi:[1,0,1]
	v_pk_fma_f32 v[62:63], v[136:137], v[142:143], v[62:63] op_sel_hi:[1,0,1]
	v_add_f32_dpp v10, v10, v10 quad_perm:[2,3,0,1] row_mask:0xf bank_mask:0xf bound_ctrl:1
	ds_read_b128 v[40:43], v86 offset:44800
	ds_read_b128 v[44:47], v84 offset:44800
	v_add_f32_dpp v10, v10, v10 row_ror:4 row_mask:0xf bank_mask:0xf bound_ctrl:1
	ds_read_b128 v[48:51], v83 offset:45312
	ds_read_b128 v[52:55], v83 offset:45568
	v_add_f32_dpp v11, v10, v10 row_ror:8 row_mask:0xf bank_mask:0xf bound_ctrl:1
	ds_read_b128 v[56:59], v83 offset:45824
	ds_read_b64 v[60:61], v85 offset:46080
	v_mov_b32_dpp v12, v11 quad_perm:[0,0,2,2] row_mask:0xf bank_mask:0xf bound_ctrl:1
	v_pk_fma_f32 v[16:17], v[138:139], v[12:13], v[14:15] op_sel_hi:[1,0,1] neg_lo:[1,0,0] neg_hi:[1,0,0]
	v_pk_fma_f32 v[78:79], v[140:141], v[12:13], v[62:63] op_sel_hi:[1,0,1] neg_lo:[1,0,0] neg_hi:[1,0,0]
	v_fmac_f32_e32 v11, v142, v143
	v_cndmask_b32_e64 v87, v87, v11, s[18:19]
	s_and_saveexec_b64 s[0:1], s[2:3]
	ds_write_b32 v94, v87 offset:1024
	s_or_b64 exec, exec, s[0:1]
	s_waitcnt lgkmcnt(6)
	v_pk_mul_f32 v[4:5], v[18:19], v[16:17]
	v_pk_mul_f32 v[6:7], v[22:23], v[16:17]
	v_pk_fma_f32 v[4:5], v[20:21], v[78:79], v[4:5]
	v_pk_fma_f32 v[6:7], v[24:25], v[78:79], v[6:7]
	v_add_f32_e32 v2, v4, v5
	v_pk_add_f32 v[8:9], v[6:7], v[6:7] op_sel:[0,1] op_sel_hi:[1,0]
	v_pk_mul_f32 v[14:15], v[26:27], v[16:17]
	v_pk_mul_f32 v[62:63], v[28:29], v[78:79]
	v_add_f32_dpp v10, v8, v2 quad_perm:[1,0,3,2] row_mask:0xf bank_mask:0xf bound_ctrl:1
	v_pk_fma_f32 v[14:15], v[30:31], v[38:39], v[14:15] op_sel_hi:[1,0,1]
	v_pk_fma_f32 v[62:63], v[32:33], v[38:39], v[62:63] op_sel_hi:[1,0,1]
	v_add_f32_dpp v10, v10, v10 quad_perm:[2,3,0,1] row_mask:0xf bank_mask:0xf bound_ctrl:1
	ds_read_b128 v[100:103], v86 offset:46592
	ds_read_b128 v[104:107], v84 offset:46592
	v_add_f32_dpp v10, v10, v10 row_ror:4 row_mask:0xf bank_mask:0xf bound_ctrl:1
	ds_read_b128 v[108:111], v83 offset:47104
	ds_read_b128 v[112:115], v83 offset:47360
	v_add_f32_dpp v11, v10, v10 row_ror:8 row_mask:0xf bank_mask:0xf bound_ctrl:1
	ds_read_b128 v[116:119], v83 offset:47616
	ds_read_b64 v[120:121], v85 offset:47872
	v_mov_b32_dpp v12, v11 quad_perm:[0,0,2,2] row_mask:0xf bank_mask:0xf bound_ctrl:1
	v_pk_fma_f32 v[16:17], v[34:35], v[12:13], v[14:15] op_sel_hi:[1,0,1] neg_lo:[1,0,0] neg_hi:[1,0,0]
	v_pk_fma_f32 v[78:79], v[36:37], v[12:13], v[62:63] op_sel_hi:[1,0,1] neg_lo:[1,0,0] neg_hi:[1,0,0]
	v_fmac_f32_e32 v11, v38, v39
	v_cndmask_b32_e64 v87, v87, v11, s[4:5]
	s_waitcnt lgkmcnt(6)
	v_pk_mul_f32 v[4:5], v[40:41], v[16:17]
	v_pk_mul_f32 v[6:7], v[44:45], v[16:17]
	v_pk_fma_f32 v[4:5], v[42:43], v[78:79], v[4:5]
	v_pk_fma_f32 v[6:7], v[46:47], v[78:79], v[6:7]
	v_add_f32_e32 v2, v4, v5
	v_pk_add_f32 v[8:9], v[6:7], v[6:7] op_sel:[0,1] op_sel_hi:[1,0]
	v_pk_mul_f32 v[14:15], v[48:49], v[16:17]
	v_pk_mul_f32 v[62:63], v[50:51], v[78:79]
	v_add_f32_dpp v10, v8, v2 quad_perm:[1,0,3,2] row_mask:0xf bank_mask:0xf bound_ctrl:1
	v_pk_fma_f32 v[14:15], v[52:53], v[60:61], v[14:15] op_sel_hi:[1,0,1]
	v_pk_fma_f32 v[62:63], v[54:55], v[60:61], v[62:63] op_sel_hi:[1,0,1]
	v_add_f32_dpp v10, v10, v10 quad_perm:[2,3,0,1] row_mask:0xf bank_mask:0xf bound_ctrl:1
	ds_read_b128 v[122:125], v86 offset:48384
	ds_read_b128 v[126:129], v84 offset:48384
	v_add_f32_dpp v10, v10, v10 row_ror:4 row_mask:0xf bank_mask:0xf bound_ctrl:1
	ds_read_b128 v[130:133], v83 offset:48896
	ds_read_b128 v[134:137], v83 offset:49152
	v_add_f32_dpp v11, v10, v10 row_ror:8 row_mask:0xf bank_mask:0xf bound_ctrl:1
	ds_read_b128 v[138:141], v83 offset:49408
	ds_read_b64 v[142:143], v85 offset:49664
	v_mov_b32_dpp v12, v11 quad_perm:[0,0,2,2] row_mask:0xf bank_mask:0xf bound_ctrl:1
	v_pk_fma_f32 v[16:17], v[56:57], v[12:13], v[14:15] op_sel_hi:[1,0,1] neg_lo:[1,0,0] neg_hi:[1,0,0]
	v_pk_fma_f32 v[78:79], v[58:59], v[12:13], v[62:63] op_sel_hi:[1,0,1] neg_lo:[1,0,0] neg_hi:[1,0,0]
	v_fmac_f32_e32 v11, v60, v61
	v_cndmask_b32_e64 v87, v87, v11, s[6:7]
	s_waitcnt lgkmcnt(6)
	v_pk_mul_f32 v[4:5], v[100:101], v[16:17]
	v_pk_mul_f32 v[6:7], v[104:105], v[16:17]
	v_pk_fma_f32 v[4:5], v[102:103], v[78:79], v[4:5]
	v_pk_fma_f32 v[6:7], v[106:107], v[78:79], v[6:7]
	v_add_f32_e32 v2, v4, v5
	v_pk_add_f32 v[8:9], v[6:7], v[6:7] op_sel:[0,1] op_sel_hi:[1,0]
	v_pk_mul_f32 v[14:15], v[108:109], v[16:17]
	v_pk_mul_f32 v[62:63], v[110:111], v[78:79]
	v_add_f32_dpp v10, v8, v2 quad_perm:[1,0,3,2] row_mask:0xf bank_mask:0xf bound_ctrl:1
	v_pk_fma_f32 v[14:15], v[112:113], v[120:121], v[14:15] op_sel_hi:[1,0,1]
	v_pk_fma_f32 v[62:63], v[114:115], v[120:121], v[62:63] op_sel_hi:[1,0,1]
	v_add_f32_dpp v10, v10, v10 quad_perm:[2,3,0,1] row_mask:0xf bank_mask:0xf bound_ctrl:1
	ds_read_b128 v[18:21], v86 offset:50176
	ds_read_b128 v[22:25], v84 offset:50176
	v_add_f32_dpp v10, v10, v10 row_ror:4 row_mask:0xf bank_mask:0xf bound_ctrl:1
	ds_read_b128 v[26:29], v83 offset:50688
	ds_read_b128 v[30:33], v83 offset:50944
	v_add_f32_dpp v11, v10, v10 row_ror:8 row_mask:0xf bank_mask:0xf bound_ctrl:1
	ds_read_b128 v[34:37], v83 offset:51200
	ds_read_b64 v[38:39], v85 offset:51456
	v_mov_b32_dpp v12, v11 quad_perm:[0,0,2,2] row_mask:0xf bank_mask:0xf bound_ctrl:1
	v_pk_fma_f32 v[16:17], v[116:117], v[12:13], v[14:15] op_sel_hi:[1,0,1] neg_lo:[1,0,0] neg_hi:[1,0,0]
	v_pk_fma_f32 v[78:79], v[118:119], v[12:13], v[62:63] op_sel_hi:[1,0,1] neg_lo:[1,0,0] neg_hi:[1,0,0]
	v_fmac_f32_e32 v11, v120, v121
	v_cndmask_b32_e64 v87, v87, v11, s[8:9]
	s_waitcnt lgkmcnt(6)
; #define SC_LD(S, X) do { const LAS float* q_ = sb + (S) * STEPF; X##kk = *(const LAS f32x4*)(q_ + lo_own); X##wr = *(const LAS f32x4*)(q_ + lo_oth); X##w = *(const LAS f32x4*)(q_ + 128 + 4 * cgp); \
;         X##k = *(const LAS f32x4*)(q_ + 192 + 4 * cgp); X##b = *(const LAS f32x4*)(q_ + 256 + 4 * cgp); X##vk = *(const LAS f32x2*)(q_ + 320 + 2 * row); } while (0)
; __device__ __forceinline__ void scan_phase(const Ctx& F, const float* sbg) {
;     ...
;                 SC_LD(0, A);
; #pragma unroll
;                 for (int s = 0; s < T; s += 2) { SC_LD(s + 1, B); SC_ST(s, A); if (s + 2 < T) SC_LD(s + 2, A); SC_ST(s + 1, B); }
	v_pk_mul_f32 v[4:5], v[122:123], v[16:17]
	v_pk_mul_f32 v[6:7], v[126:127], v[16:17]
	v_pk_fma_f32 v[4:5], v[124:125], v[78:79], v[4:5]
	v_pk_fma_f32 v[6:7], v[128:129], v[78:79], v[6:7]
	v_add_f32_e32 v2, v4, v5
	v_pk_add_f32 v[8:9], v[6:7], v[6:7] op_sel:[0,1] op_sel_hi:[1,0]
	v_pk_mul_f32 v[14:15], v[130:131], v[16:17]
	v_pk_mul_f32 v[62:63], v[132:133], v[78:79]
	v_add_f32_dpp v10, v8, v2 quad_perm:[1,0,3,2] row_mask:0xf bank_mask:0xf bound_ctrl:1
	v_pk_fma_f32 v[14:15], v[134:135], v[142:143], v[14:15] op_sel_hi:[1,0,1]
	v_pk_fma_f32 v[62:63], v[136:137], v[142:143], v[62:63] op_sel_hi:[1,0,1]
	v_add_f32_dpp v10, v10, v10 quad_perm:[2,3,0,1] row_mask:0xf bank_mask:0xf bound_ctrl:1
	ds_read_b128 v[40:43], v86 offset:51968
	ds_read_b128 v[44:47], v84 offset:51968
	v_add_f32_dpp v10, v10, v10 row_ror:4 row_mask:0xf bank_mask:0xf bound_ctrl:1
	ds_read_b128 v[48:51], v83 offset:52480
	ds_read_b128 v[52:55], v83 offset:52736
	v_add_f32_dpp v11, v10, v10 row_ror:8 row_mask:0xf bank_mask:0xf bound_ctrl:1
	ds_read_b128 v[56:59], v83 offset:52992
	ds_read_b64 v[60:61], v85 offset:53248
	v_mov_b32_dpp v12, v11 quad_perm:[0,0,2,2] row_mask:0xf bank_mask:0xf bound_ctrl:1
	v_pk_fma_f32 v[16:17], v[138:139], v[12:13], v[14:15] op_sel_hi:[1,0,1] neg_lo:[1,0,0] neg_hi:[1,0,0]
	v_pk_fma_f32 v[78:79], v[140:141], v[12:13], v[62:63] op_sel_hi:[1,0,1] neg_lo:[1,0,0] neg_hi:[1,0,0]
	v_fmac_f32_e32 v11, v142, v143
	v_cndmask_b32_e64 v87, v87, v11, s[10:11]
	s_waitcnt lgkmcnt(6)
	v_pk_mul_f32 v[4:5], v[18:19], v[16:17]
	v_pk_mul_f32 v[6:7], v[22:23], v[16:17]
	v_pk_fma_f32 v[4:5], v[20:21], v[78:79], v[4:5]
	v_pk_fma_f32 v[6:7], v[24:25], v[78:79], v[6:7]
	v_add_f32_e32 v2, v4, v5
	v_pk_add_f32 v[8:9], v[6:7], v[6:7] op_sel:[0,1] op_sel_hi:[1,0]
	v_pk_mul_f32 v[14:15], v[26:27], v[16:17]
	v_pk_mul_f32 v[62:63], v[28:29], v[78:79]
	v_add_f32_dpp v10, v8, v2 quad_perm:[1,0,3,2] row_mask:0xf bank_mask:0xf bound_ctrl:1
	v_pk_fma_f32 v[14:15], v[30:31], v[38:39], v[14:15] op_sel_hi:[1,0,1]
	v_pk_fma_f32 v[62:63], v[32:33], v[38:39], v[62:63] op_sel_hi:[1,0,1]
	v_add_f32_dpp v10, v10, v10 quad_perm:[2,3,0,1] row_mask:0xf bank_mask:0xf bound_ctrl:1
	ds_read_b128 v[100:103], v86 offset:53760
	ds_read_b128 v[104:107], v84 offset:53760
	v_add_f32_dpp v10, v10, v10 row_ror:4 row_mask:0xf bank_mask:0xf bound_ctrl:1
	ds_read_b128 v[108:111], v83 offset:54272
	ds_read_b128 v[112:115], v83 offset:54528
	v_add_f32_dpp v11, v10, v10 row_ror:8 row_mask:0xf bank_mask:0xf bound_ctrl:1
	ds_read_b128 v[116:119], v83 offset:54784
	ds_read_b64 v[120:121], v85 offset:55040
	v_mov_b32_dpp v12, v11 quad_perm:[0,0,2,2] row_mask:0xf bank_mask:0xf bound_ctrl:1
	v_pk_fma_f32 v[16:17], v[34:35], v[12:13], v[14:15] op_sel_hi:[1,0,1] neg_lo:[1,0,0] neg_hi:[1,0,0]
	v_pk_fma_f32 v[78:79], v[36:37], v[12:13], v[62:63] op_sel_hi:[1,0,1] neg_lo:[1,0,0] neg_hi:[1,0,0]
	v_fmac_f32_e32 v11, v38, v39
	v_cndmask_b32_e64 v87, v87, v11, s[12:13]
	s_waitcnt lgkmcnt(6)
	v_pk_mul_f32 v[4:5], v[40:41], v[16:17]
	v_pk_mul_f32 v[6:7], v[44:45], v[16:17]
	v_pk_fma_f32 v[4:5], v[42:43], v[78:79], v[4:5]
	v_pk_fma_f32 v[6:7], v[46:47], v[78:79], v[6:7]
	v_add_f32_e32 v2, v4, v5
	v_pk_add_f32 v[8:9], v[6:7], v[6:7] op_sel:[0,1] op_sel_hi:[1,0]
	v_pk_mul_f32 v[14:15], v[48:49], v[16:17]
	v_pk_mul_f32 v[62:63], v[50:51], v[78:79]
	v_add_f32_dpp v10, v8, v2 quad_perm:[1,0,3,2] row_mask:0xf bank_mask:0xf bound_ctrl:1
	v_pk_fma_f32 v[14:15], v[52:53], v[60:61], v[14:15] op_sel_hi:[1,0,1]
	v_pk_fma_f32 v[62:63], v[54:55], v[60:61], v[62:63] op_sel_hi:[1,0,1]
	v_add_f32_dpp v10, v10, v10 quad_perm:[2,3,0,1] row_mask:0xf bank_mask:0xf bound_ctrl:1
	ds_read_b128 v[122:125], v86 offset:55552
	ds_read_b128 v[126:129], v84 offset:55552
	v_add_f32_dpp v10, v10, v10 row_ror:4 row_mask:0xf bank_mask:0xf bound_ctrl:1
	ds_read_b128 v[130:133], v83 offset:56064
	ds_read_b128 v[134:137], v83 offset:56320
	v_add_f32_dpp v11, v10, v10 row_ror:8 row_mask:0xf bank_mask:0xf bound_ctrl:1
	ds_read_b128 v[138:141], v83 offset:56576
	ds_read_b64 v[142:143], v85 offset:56832
	v_mov_b32_dpp v12, v11 quad_perm:[0,0,2,2] row_mask:0xf bank_mask:0xf bound_ctrl:1
	v_pk_fma_f32 v[16:17], v[56:57], v[12:13], v[14:15] op_sel_hi:[1,0,1] neg_lo:[1,0,0] neg_hi:[1,0,0]
	v_pk_fma_f32 v[78:79], v[58:59], v[12:13], v[62:63] op_sel_hi:[1,0,1] neg_lo:[1,0,0] neg_hi:[1,0,0]
	v_fmac_f32_e32 v11, v60, v61
	v_cndmask_b32_e64 v87, v87, v11, s[14:15]
	s_waitcnt lgkmcnt(6)
; #define LAS __attribute__((address_space(3)))
; #define SC_LD(S, X) do { const LAS float* q_ = sb + (S) * STEPF; X##kk = *(const LAS f32x4*)(q_ + lo_own); X##wr = *(const LAS f32x4*)(q_ + lo_oth); X##w = *(const LAS f32x4*)(q_ + 128 + 4 * cgp); \
;         X##k = *(const LAS f32x4*)(q_ + 192 + 4 * cgp); X##b = *(const LAS f32x4*)(q_ + 256 + 4 * cgp); X##vk = *(const LAS f32x2*)(q_ + 320 + 2 * row); } while (0)
; __device__ __forceinline__ void scan_phase(const Ctx& F, const float* sbg) {
;     ...
;                 const LAS float* sb = bufs + (ch & 1) * (T * STEPF); LAS float* yb = ybufs + (ch & 1) * (T * 16) + rl;
;     ...
;                 for (int s = 0; s < T; s += 2) { SC_LD(s + 1, B); SC_ST(s, A); if (s + 2 < T) SC_LD(s + 2, A); SC_ST(s + 1, B); }
;     ...
;                 asm volatile("s_waitcnt lgkmcnt(0)\n\ts_barrier" ::: "memory");
	v_pk_mul_f32 v[4:5], v[100:101], v[16:17]
	v_pk_mul_f32 v[6:7], v[104:105], v[16:17]
	v_pk_fma_f32 v[4:5], v[102:103], v[78:79], v[4:5]
	v_pk_fma_f32 v[6:7], v[106:107], v[78:79], v[6:7]
	v_add_f32_e32 v2, v4, v5
	v_pk_add_f32 v[8:9], v[6:7], v[6:7] op_sel:[0,1] op_sel_hi:[1,0]
	v_pk_mul_f32 v[14:15], v[108:109], v[16:17]
	v_pk_mul_f32 v[62:63], v[110:111], v[78:79]
	v_add_f32_dpp v10, v8, v2 quad_perm:[1,0,3,2] row_mask:0xf bank_mask:0xf bound_ctrl:1
	v_pk_fma_f32 v[14:15], v[112:113], v[120:121], v[14:15] op_sel_hi:[1,0,1]
	v_pk_fma_f32 v[62:63], v[114:115], v[120:121], v[62:63] op_sel_hi:[1,0,1]
	v_add_f32_dpp v10, v10, v10 quad_perm:[2,3,0,1] row_mask:0xf bank_mask:0xf bound_ctrl:1
	s_nop 1
	v_add_f32_dpp v10, v10, v10 row_ror:4 row_mask:0xf bank_mask:0xf bound_ctrl:1
	s_nop 1
	v_add_f32_dpp v11, v10, v10 row_ror:8 row_mask:0xf bank_mask:0xf bound_ctrl:1
	s_nop 1
	v_mov_b32_dpp v12, v11 quad_perm:[0,0,2,2] row_mask:0xf bank_mask:0xf bound_ctrl:1
	v_pk_fma_f32 v[16:17], v[116:117], v[12:13], v[14:15] op_sel_hi:[1,0,1] neg_lo:[1,0,0] neg_hi:[1,0,0]
	v_pk_fma_f32 v[78:79], v[118:119], v[12:13], v[62:63] op_sel_hi:[1,0,1] neg_lo:[1,0,0] neg_hi:[1,0,0]
	v_fmac_f32_e32 v11, v120, v121
	v_cndmask_b32_e64 v87, v87, v11, s[16:17]
	s_waitcnt lgkmcnt(0)
	v_pk_mul_f32 v[4:5], v[122:123], v[16:17]
	v_pk_mul_f32 v[6:7], v[126:127], v[16:17]
	v_pk_fma_f32 v[4:5], v[124:125], v[78:79], v[4:5]
	v_pk_fma_f32 v[6:7], v[128:129], v[78:79], v[6:7]
	v_add_f32_e32 v2, v4, v5
	v_pk_add_f32 v[8:9], v[6:7], v[6:7] op_sel:[0,1] op_sel_hi:[1,0]
	v_pk_mul_f32 v[14:15], v[130:131], v[16:17]
	v_pk_mul_f32 v[62:63], v[132:133], v[78:79]
	v_add_f32_dpp v10, v8, v2 quad_perm:[1,0,3,2] row_mask:0xf bank_mask:0xf bound_ctrl:1
	v_pk_fma_f32 v[14:15], v[134:135], v[142:143], v[14:15] op_sel_hi:[1,0,1]
	v_pk_fma_f32 v[62:63], v[136:137], v[142:143], v[62:63] op_sel_hi:[1,0,1]
	v_add_f32_dpp v10, v10, v10 quad_perm:[2,3,0,1] row_mask:0xf bank_mask:0xf bound_ctrl:1
	s_nop 1
	v_add_f32_dpp v10, v10, v10 row_ror:4 row_mask:0xf bank_mask:0xf bound_ctrl:1
	s_nop 1
	v_add_f32_dpp v11, v10, v10 row_ror:8 row_mask:0xf bank_mask:0xf bound_ctrl:1
	s_nop 1
	v_mov_b32_dpp v12, v11 quad_perm:[0,0,2,2] row_mask:0xf bank_mask:0xf bound_ctrl:1
	v_pk_fma_f32 v[16:17], v[138:139], v[12:13], v[14:15] op_sel_hi:[1,0,1] neg_lo:[1,0,0] neg_hi:[1,0,0]
	v_pk_fma_f32 v[78:79], v[140:141], v[12:13], v[62:63] op_sel_hi:[1,0,1] neg_lo:[1,0,0] neg_hi:[1,0,0]
	v_fmac_f32_e32 v11, v142, v143
	v_cndmask_b32_e64 v87, v87, v11, s[18:19]
	s_and_saveexec_b64 s[0:1], s[2:3]
	ds_write_b32 v94, v87 offset:1536
	s_or_b64 exec, exec, s[0:1]
	s_add_i32 s22, s22, 1
	s_and_b32 s0, s22, 1
	s_mul_i32 s1, s0, 0xe000
	v_lshl_add_u32 v86, v171, 2, s1
	v_lshl_add_u32 v84, v173, 2, s1
	v_lshl_add_u32 v83, v1, 2, s1
	v_lshl_add_u32 v85, v82, 2, s1
	v_lshl_add_u32 v94, s0, 11, v206
	v_add_u32_e32 v94, v94, v198
	s_waitcnt lgkmcnt(0)
	s_barrier
	s_cmpk_eq_i32 s22, 0x80
	s_cbranch_scc0 .Lscan_chunk
	s_branch .LBB0_660
